# baseline (speedup 1.0000x reference)
.LBB0_166:
.LBB0_167:
.LBB0_169:
	s_cmp_lt_u32 s97, 64
	s_cbranch_scc1 .Lattn_pf_a0
	s_setprio 0
	s_branch .Lattn_pf_j0
.Lattn_pf_a0:
	s_setprio 2
.Lattn_pf_j0:
	s_add_i32 s8, s98, 0xffffff40
	s_cmp_le_i32 s8, s74
	s_waitcnt lgkmcnt(5)
	v_mfma_f32_32x32x16_bf16 v[82:97], v[66:69], v[98:101], 0
	s_waitcnt lgkmcnt(4)
	v_mfma_f32_32x32x16_bf16 v[82:97], v[70:73], v[102:105], v[82:97]
	s_waitcnt lgkmcnt(3)
	v_mfma_f32_32x32x16_bf16 v[82:97], v[74:77], v[106:109], v[82:97]
	s_waitcnt lgkmcnt(2)
	v_mfma_f32_32x32x16_bf16 v[82:97], v[78:81], v[110:113], v[82:97]
	s_waitcnt lgkmcnt(1)
	v_mfma_f32_32x32x16_bf16 v[66:81], v[212:215], v[98:101], 0
	ds_read_b128 v[212:215], v227 offset:8192
	s_waitcnt lgkmcnt(1)
	v_mfma_f32_32x32x16_bf16 v[66:81], v[250:253], v[102:105], v[66:81]
	ds_read_b128 v[250:253], v228 offset:8192
	s_waitcnt lgkmcnt(1)
	v_mfma_f32_32x32x16_bf16 v[66:81], v[212:215], v[106:109], v[66:81]
	s_waitcnt lgkmcnt(0)
	v_mfma_f32_32x32x16_bf16 v[66:81], v[250:253], v[110:113], v[66:81]
	s_cbranch_scc1 .LBB0_171
	v_cmp_gt_i32_e64 s[68:69], 26, v231
	v_cmp_gt_i32_e64 s[70:71], 27, v231
	v_cmp_gt_i32_e64 s[66:67], 25, v231
	s_and_b64 s[68:69], s[70:71], s[68:69]
	v_cmp_gt_i32_e64 s[64:65], 24, v231
	s_and_b64 s[66:67], s[68:69], s[66:67]
	v_cmp_gt_i32_e64 s[62:63], 19, v231
	s_and_b64 s[64:65], s[66:67], s[64:65]
	v_cmp_gt_i32_e64 s[60:61], 18, v231
	s_and_b64 s[62:63], s[64:65], s[62:63]
	v_cmp_gt_i32_e64 s[58:59], 17, v231
	s_and_b64 s[60:61], s[62:63], s[60:61]
	v_cmp_gt_i32_e64 s[56:57], 16, v231
	s_and_b64 s[58:59], s[60:61], s[58:59]
	v_cmp_gt_i32_e64 s[54:55], 11, v231
	s_and_b64 s[56:57], s[58:59], s[56:57]
	v_cmp_gt_i32_e64 s[52:53], 10, v231
	s_and_b64 s[54:55], s[56:57], s[54:55]
	v_cmp_gt_i32_e64 s[50:51], 9, v231
	s_and_b64 s[52:53], s[54:55], s[52:53]
	v_cmp_gt_i32_e64 s[48:49], 8, v231
	s_and_b64 s[50:51], s[52:53], s[50:51]
	v_cmp_gt_i32_e64 s[46:47], 3, v231
	s_and_b64 s[48:49], s[50:51], s[48:49]
	v_cmp_gt_i32_e64 s[44:45], 2, v231
	s_and_b64 s[46:47], s[48:49], s[46:47]
	v_cmp_gt_i32_e64 s[42:43], 1, v231
	s_and_b64 s[44:45], s[46:47], s[44:45]
	v_cmp_gt_i32_e64 s[40:41], 0, v231
	s_and_b64 s[42:43], s[44:45], s[42:43]
	s_and_b64 s[40:41], s[42:43], s[40:41]
	v_cmp_gt_i32_e64 s[36:37], 58, v231
	v_cndmask_b32_e64 v82, v82, v210, s[40:41]
	v_cmp_gt_i32_e64 s[40:41], 59, v231
	v_cmp_gt_i32_e64 s[34:35], 57, v231
	s_and_b64 s[36:37], s[40:41], s[36:37]
	v_cmp_gt_i32_e64 s[30:31], 56, v231
	s_and_b64 s[34:35], s[36:37], s[34:35]
	v_cmp_gt_i32_e64 s[28:29], 51, v231
	s_and_b64 s[30:31], s[34:35], s[30:31]
	v_cmp_gt_i32_e64 s[26:27], 50, v231
	s_and_b64 s[28:29], s[30:31], s[28:29]
	v_cmp_gt_i32_e64 s[24:25], 49, v231
	s_and_b64 s[26:27], s[28:29], s[26:27]
	v_cmp_gt_i32_e64 s[22:23], 48, v231
	s_and_b64 s[24:25], s[26:27], s[24:25]
	v_cmp_gt_i32_e64 s[20:21], 43, v231
	s_and_b64 s[22:23], s[24:25], s[22:23]
	v_cmp_gt_i32_e64 s[18:19], 42, v231
	s_and_b64 s[20:21], s[22:23], s[20:21]
	v_cmp_gt_i32_e64 s[16:17], 41, v231
	s_and_b64 s[18:19], s[20:21], s[18:19]
	v_cmp_gt_i32_e64 s[14:15], 40, v231
	s_and_b64 s[16:17], s[18:19], s[16:17]
	v_cmp_gt_i32_e64 s[12:13], 35, v231
	s_and_b64 s[14:15], s[16:17], s[14:15]
	v_cmp_gt_i32_e64 s[10:11], 34, v231
	s_and_b64 s[12:13], s[14:15], s[12:13]
	v_cmp_gt_i32_e64 s[8:9], 33, v231
	s_and_b64 s[10:11], s[12:13], s[10:11]
	v_cmp_gt_i32_e32 vcc, 32, v231
	s_and_b64 s[8:9], s[10:11], s[8:9]
	s_and_b64 vcc, s[8:9], vcc
	v_cndmask_b32_e64 v97, v97, v210, s[70:71]
	v_cndmask_b32_e64 v96, v96, v210, s[68:69]
	v_cndmask_b32_e64 v95, v95, v210, s[66:67]
	v_cndmask_b32_e64 v94, v94, v210, s[64:65]
	v_cndmask_b32_e64 v93, v93, v210, s[62:63]
	v_cndmask_b32_e64 v92, v92, v210, s[60:61]
	v_cndmask_b32_e64 v91, v91, v210, s[58:59]
	v_cndmask_b32_e64 v90, v90, v210, s[56:57]
	v_cndmask_b32_e64 v89, v89, v210, s[54:55]
	v_cndmask_b32_e64 v88, v88, v210, s[52:53]
	v_cndmask_b32_e64 v87, v87, v210, s[50:51]
	v_cndmask_b32_e64 v86, v86, v210, s[48:49]
	v_cndmask_b32_e64 v85, v85, v210, s[46:47]
	v_cndmask_b32_e64 v84, v84, v210, s[44:45]
	v_cndmask_b32_e64 v83, v83, v210, s[42:43]
	v_cndmask_b32_e64 v81, v81, v210, s[40:41]
	v_cndmask_b32_e64 v80, v80, v210, s[36:37]
	v_cndmask_b32_e64 v79, v79, v210, s[34:35]
	v_cndmask_b32_e64 v78, v78, v210, s[30:31]
	v_cndmask_b32_e64 v77, v77, v210, s[28:29]
	v_cndmask_b32_e64 v76, v76, v210, s[26:27]
	v_cndmask_b32_e64 v75, v75, v210, s[24:25]
	v_cndmask_b32_e64 v74, v74, v210, s[22:23]
	v_cndmask_b32_e64 v73, v73, v210, s[20:21]
	v_cndmask_b32_e64 v72, v72, v210, s[18:19]
	v_cndmask_b32_e64 v71, v71, v210, s[16:17]
	v_cndmask_b32_e64 v70, v70, v210, s[14:15]
	v_cndmask_b32_e64 v69, v69, v210, s[12:13]
	v_cndmask_b32_e64 v68, v68, v210, s[10:11]
	v_cndmask_b32_e64 v67, v67, v210, s[8:9]
	v_cndmask_b32_e32 v66, v66, v210, vcc

.LBB0_179:
	s_cmp_lt_u32 s97, 64
	s_cbranch_scc1 .Lattn_pf_a1
	s_setprio 2
	s_branch .Lattn_pf_j1

.LBB0_190:
	s_cmp_lt_u32 s97, 64
	s_cbranch_scc1 .Lattn_pf_a2
	s_setprio 0
	s_branch .Lattn_pf_j2
